# scan compute: packed f32 ops (v_pk_mul/v_pk_fma/v_pk_add) for decay and forward substitution, 64-bit coefficient loads, helper waves skip the compute-only address setup
# speedup vs baseline: 1.0084x; 1.0084x over previous
.LBB0_672:
	s_add_i32 s22, s65, 1
	s_and_b32 s23, s65, 1
	s_mov_b32 s24, 0
	v_and_b32_e32 v224, 63, v64
	v_and_b32_e32 v233, 15, v224
	v_lshrrev_b32_e32 v234, 4, v224
	s_mov_b32 s98, 0
	s_mov_b32 s99, -1
	v_mov_b32_e32 v235, 0
	s_cmp_lg_u32 s65, 0
	s_cbranch_scc1 .Lmy_f_main
	s_bfe_u32 s96, s62, 0x20006
	s_lshl_b32 s100, s96, 11
	v_lshl_add_u32 v72, v224, 2, s100
	s_mul_i32 s97, s96, 0x2700
	s_cmp_gt_u32 s96, 1
	s_cselect_b32 s101, 0x1300, 0
	s_add_i32 s97, s97, s101
	s_add_i32 s97, s97, 0x1c000
	ds_read_b32 v80, v72
	ds_read_b32 v81, v72 offset:256
	ds_read_b32 v82, v72 offset:512
	ds_read_b32 v83, v72 offset:768
	ds_read_b32 v84, v72 offset:1024
	ds_read_b32 v85, v72 offset:1280
	ds_read_b32 v86, v72 offset:1536
	ds_read_b32 v87, v72 offset:1792
	s_cmpk_ge_u32 s62, 0x100
	s_cbranch_scc1 .Lmy_ck_drB_a
	ds_read_b32 v88, v72 offset:8192
	ds_read_b32 v89, v72 offset:8448
	ds_read_b32 v90, v72 offset:8704
	ds_read_b32 v91, v72 offset:8960
	ds_read_b32 v92, v72 offset:9216
	ds_read_b32 v93, v72 offset:9472
	ds_read_b32 v94, v72 offset:9728
	ds_read_b32 v95, v72 offset:9984
	ds_read_b32 v96, v72 offset:32768
	ds_read_b32 v97, v72 offset:33024
	ds_read_b32 v98, v72 offset:33280
	ds_read_b32 v99, v72 offset:33536
	ds_read_b32 v100, v72 offset:33792
	ds_read_b32 v101, v72 offset:34048
	ds_read_b32 v102, v72 offset:34304
	ds_read_b32 v103, v72 offset:34560
	v_and_b32_e32 v74, 3, v224
	v_bfe_u32 v75, v224, 2, 2
	v_lshrrev_b32_e32 v76, 4, v224
	v_lshlrev_b32_e32 v74, 2, v74
	v_lshl_add_u32 v74, v75, 8, v74
	v_lshl_add_u32 v74, v76, 10, v74
	s_add_i32 s100, s97, 0x0
	v_add_u32_e32 v74, s100, v74
	v_xor_b32_e32 v76, 0, v75
	v_xor_b32_e32 v77, 1, v75
	v_xor_b32_e32 v78, 2, v75
	v_xor_b32_e32 v79, 3, v75
	v_lshl_add_u32 v76, v76, 4, v74
	v_lshl_add_u32 v77, v77, 4, v74
	v_lshl_add_u32 v78, v78, 4, v74
	v_lshl_add_u32 v79, v79, 4, v74
	s_waitcnt lgkmcnt(15)
	v_mov_b32_e32 v104, v80
	v_mul_f32_e32 v105, v104, v81
	v_mul_f32_e32 v106, v105, v82
	v_mul_f32_e32 v107, v106, v83
	v_mul_f32_e32 v108, v107, v84
	v_mul_f32_e32 v109, v108, v85
	v_mul_f32_e32 v110, v109, v86
	v_mul_f32_e32 v111, v110, v87
	v_mov_b32_e32 v112, v88
	s_waitcnt lgkmcnt(14)
	v_mul_f32_e32 v113, v104, v89
	s_waitcnt lgkmcnt(13)
	v_mul_f32_e32 v114, v105, v90
	s_waitcnt lgkmcnt(12)
	v_mul_f32_e32 v115, v106, v91
	s_waitcnt lgkmcnt(11)
	v_mul_f32_e32 v116, v107, v92
	s_waitcnt lgkmcnt(10)
	v_mul_f32_e32 v117, v108, v93
	s_waitcnt lgkmcnt(9)
	v_mul_f32_e32 v118, v109, v94
	s_waitcnt lgkmcnt(8)
	v_mul_f32_e32 v119, v110, v95
	s_waitcnt lgkmcnt(7)
	v_mul_f32_e32 v120, v104, v96
	s_waitcnt lgkmcnt(6)
	v_mul_f32_e32 v121, v105, v97
	s_waitcnt lgkmcnt(5)
	v_mul_f32_e32 v122, v106, v98
	s_waitcnt lgkmcnt(4)
	v_mul_f32_e32 v123, v107, v99
	s_waitcnt lgkmcnt(3)
	v_mul_f32_e32 v124, v108, v100
	s_waitcnt lgkmcnt(2)
	v_mul_f32_e32 v125, v109, v101
	s_waitcnt lgkmcnt(1)
	v_mul_f32_e32 v126, v110, v102
	s_waitcnt lgkmcnt(0)
	v_mul_f32_e32 v127, v111, v103
	ds_write_b32 v76, v112
	ds_write_b32 v77, v113
	ds_write_b32 v78, v114
	ds_write_b32 v79, v115
	ds_write_b32 v76, v116 offset:64
	ds_write_b32 v77, v117 offset:64
	ds_write_b32 v78, v118 offset:64
	ds_write_b32 v79, v119 offset:64
	ds_write_b32 v76, v120 offset:128
	ds_write_b32 v77, v121 offset:128
	ds_write_b32 v78, v122 offset:128
	ds_write_b32 v79, v123 offset:128
	ds_write_b32 v76, v124 offset:192
	ds_write_b32 v77, v125 offset:192
	ds_write_b32 v78, v126 offset:192
	ds_write_b32 v79, v127 offset:192
	s_branch .Lmy_ck_drE_a

.Lmy_f_main:
	s_cmpk_ge_u32 s62, 0x100
	s_cbranch_scc1 .Lmy_f_hlp
	s_cmp_lg_u32 s65, 0
	s_cbranch_scc1 .Lmy_ck_nz
	v_mov_b32_e32 v208, 0
	v_mov_b32_e32 v209, 0
	v_mov_b32_e32 v210, 0
	v_mov_b32_e32 v211, 0
	v_mov_b32_e32 v212, 0
	v_mov_b32_e32 v213, 0
	v_mov_b32_e32 v214, 0
	v_mov_b32_e32 v215, 0
	v_mov_b32_e32 v216, 0
	v_mov_b32_e32 v217, 0
	v_mov_b32_e32 v218, 0
	v_mov_b32_e32 v219, 0
	v_mov_b32_e32 v220, 0
	v_mov_b32_e32 v221, 0
	v_mov_b32_e32 v222, 0
	v_mov_b32_e32 v223, 0
.Lmy_ck_nz:
	s_mov_b32 s100, 0xe000
	s_cmp_eq_u32 s23, 0
	s_cselect_b32 s100, 0x1c000, s100
	v_lshl_add_u32 v236, v224, 4, s100
	v_xor_b32_e32 v225, v224, v234
	v_lshl_add_u32 v225, v225, 4, s100
	s_add_i32 s101, s100, 0x2000
	v_lshl_add_u32 v226, v234, 4, s101
	s_add_i32 s101, s100, 0x2600
	v_mov_b32_e32 v72, s101
	v_cmp_eq_u32_e64 s[96:97], 0, v234
	s_add_i32 s101, s100, 0x2500
	v_mov_b32_e32 v73, s101
	s_add_i32 s101, s100, 0x2510
	v_mov_b32_e32 v74, s101
	v_cndmask_b32_e64 v227, v72, v73, s[96:97]
	v_cmp_eq_u32_e64 s[96:97], 1, v234
	s_add_i32 s101, s100, 0x2590
	v_mov_b32_e32 v75, s101
	v_and_b32_e32 v76, 1, v234
	v_cndmask_b32_e64 v228, v72, v74, s[96:97]
	v_cndmask_b32_e64 v229, v72, v75, s[96:97]
	v_lshlrev_b32_e32 v76, 10, v76
	v_lshl_add_u32 v76, v233, 2, v76
	v_add_u32_e32 v76, s62, v76
	s_lshl_b32 s96, s23, 13
	s_add_i32 s96, s96, 0xa000
	v_add_u32_e32 v230, s96, v76
	s_lshl_b32 s96, s23, 13
	s_add_i32 s96, s96, 0x18000
	v_add_u32_e32 v231, s96, v76
	v_add_u32_e32 v232, 48, v224
	v_and_b32_e32 v232, 63, v232
	v_lshlrev_b32_e32 v232, 2, v232
	ds_read_b128 v[80:83], v225 offset:8448
	ds_read_b32 v84, v230
	ds_read_b32 v85, v230 offset:256
	ds_read_b32 v86, v230 offset:512
	ds_read_b32 v87, v230 offset:768
	ds_read_b128 v[88:91], v225
	ds_read_b128 v[92:95], v225 offset:1024
	ds_read_b128 v[96:99], v225 offset:2048
	ds_read_b128 v[100:103], v225 offset:3072
	ds_read_b32 v104, v227 offset:4
	ds_read_b32 v105, v227 offset:76
	ds_read_b64 v[106:107], v227 offset:8
	ds_read_b64 v[108:109], v227 offset:40
	ds_read_b32 v126, v229 offset:4
	ds_read_b32 v127, v229 offset:76
	ds_read_b64 v[128:129], v229 offset:8
	ds_read_b64 v[130:131], v229 offset:40
	ds_read_b64 v[110:111], v228
	ds_read_b64 v[112:113], v228 offset:32
	ds_read_b64 v[114:115], v228 offset:64
	ds_read_b64 v[116:117], v228 offset:96
	ds_read_b64 v[118:119], v228 offset:8
	ds_read_b64 v[120:121], v228 offset:40
	ds_read_b64 v[122:123], v228 offset:72
	ds_read_b64 v[124:125], v228 offset:104
	s_waitcnt lgkmcnt(15)
	v_cndmask_b32_e64 v76, 0, v84, s[98:99]
	v_cndmask_b32_e64 v77, 0, v85, s[98:99]
	v_cndmask_b32_e64 v78, 0, v86, s[98:99]
	v_cndmask_b32_e64 v79, 0, v87, s[98:99]
	v_mfma_f32_16x16x4_f32 v[240:243], v80, v76, 0
	v_mfma_f32_16x16x4_f32 v[240:243], v81, v77, v[240:243]
	v_mfma_f32_16x16x4_f32 v[240:243], v82, v78, v[240:243]
	v_mfma_f32_16x16x4_f32 v[240:243], v83, v79, v[240:243]
	v_mfma_f32_16x16x4_f32 v[240:243], v88, v208, v[240:243]
	ds_read_b128 v[184:187], v236 offset:4096
	ds_read_b128 v[188:191], v236 offset:5120
	v_mfma_f32_16x16x4_f32 v[244:247], v89, v209, 0
	ds_read_b128 v[192:195], v236 offset:6144
	ds_read_b128 v[196:199], v236 offset:7168
	v_mfma_f32_16x16x4_f32 v[240:243], v90, v210, v[240:243]
	ds_read_b128 v[132:135], v225 offset:18432
	ds_read_b32 v136, v230 offset:2048
	v_mfma_f32_16x16x4_f32 v[244:247], v91, v211, v[244:247]
	ds_read_b32 v137, v230 offset:2304
	ds_read_b32 v138, v230 offset:2560
	v_mfma_f32_16x16x4_f32 v[240:243], v92, v212, v[240:243]
	ds_read_b32 v139, v230 offset:2816
	ds_read_b128 v[140:143], v225 offset:9984
	v_mfma_f32_16x16x4_f32 v[244:247], v93, v213, v[244:247]
	ds_read_b128 v[144:147], v225 offset:11008
	ds_read_b128 v[148:151], v225 offset:12032
	v_mfma_f32_16x16x4_f32 v[240:243], v94, v214, v[240:243]
	ds_read_b128 v[152:155], v225 offset:13056
	ds_read_b32 v156, v227 offset:9988
	v_mfma_f32_16x16x4_f32 v[244:247], v95, v215, v[244:247]
	ds_read_b32 v157, v227 offset:10060
	ds_read_b64 v[158:159], v227 offset:9992
	v_mfma_f32_16x16x4_f32 v[240:243], v96, v216, v[240:243]
	ds_read_b64 v[160:161], v227 offset:10024
	ds_read_b32 v178, v229 offset:9988
	v_mfma_f32_16x16x4_f32 v[244:247], v97, v217, v[244:247]
	ds_read_b32 v179, v229 offset:10060
	ds_read_b64 v[180:181], v229 offset:9992
	v_mfma_f32_16x16x4_f32 v[240:243], v98, v218, v[240:243]
	ds_read_b64 v[182:183], v229 offset:10024
	ds_read_b64 v[162:163], v228 offset:9984
	v_mfma_f32_16x16x4_f32 v[244:247], v99, v219, v[244:247]
	ds_read_b64 v[164:165], v228 offset:10016
	ds_read_b64 v[166:167], v228 offset:10048
	v_mfma_f32_16x16x4_f32 v[240:243], v100, v220, v[240:243]
	ds_read_b64 v[168:169], v228 offset:10080
	ds_read_b64 v[170:171], v228 offset:9992
	v_mfma_f32_16x16x4_f32 v[244:247], v101, v221, v[244:247]
	ds_read_b64 v[172:173], v228 offset:10024
	ds_read_b64 v[174:175], v228 offset:10056
	v_mfma_f32_16x16x4_f32 v[240:243], v102, v222, v[240:243]
	ds_read_b64 v[176:177], v228 offset:10088
	v_mfma_f32_16x16x4_f32 v[244:247], v103, v223, v[244:247]
	s_nop 9
	v_pk_add_f32 v[240:241], v[240:241], v[244:245]
	v_pk_add_f32 v[242:243], v[242:243], v[246:247]
	v_fmac_f32_e32 v241, v104, v240
	s_waitcnt lgkmcnt(15)
	v_pk_fma_f32 v[242:243], v[106:107], v[240:241], v[242:243] op_sel:[0,0,0] op_sel_hi:[1,0,1]
	v_pk_fma_f32 v[242:243], v[108:109], v[240:241], v[242:243] op_sel:[0,1,0] op_sel_hi:[1,1,1]
	v_fmac_f32_e32 v243, v105, v242
	ds_bpermute_b32 v204, v232, v240
	ds_bpermute_b32 v205, v232, v241
	ds_bpermute_b32 v206, v232, v242
	ds_bpermute_b32 v207, v232, v243
	ds_read_b128 v[88:91], v226
	ds_read_b128 v[92:95], v226 offset:64
	ds_read_b128 v[96:99], v226 offset:128
	ds_read_b128 v[100:103], v226 offset:192
	v_cndmask_b32_e64 v76, 0, v136, s[98:99]
	v_cndmask_b32_e64 v77, 0, v137, s[98:99]
	v_cndmask_b32_e64 v78, 0, v138, s[98:99]
	v_cndmask_b32_e64 v79, 0, v139, s[98:99]
	v_mfma_f32_16x16x4_f32 v[72:75], v132, v76, 0
	s_waitcnt lgkmcnt(6)
	v_pk_fma_f32 v[240:241], v[110:111], v[204:205], v[240:241] op_sel:[0,0,0] op_sel_hi:[1,0,1]
	v_pk_fma_f32 v[240:241], v[112:113], v[204:205], v[240:241] op_sel:[0,1,0] op_sel_hi:[1,1,1]
	s_waitcnt lgkmcnt(4)
	v_pk_fma_f32 v[240:241], v[114:115], v[206:207], v[240:241] op_sel:[0,0,0] op_sel_hi:[1,0,1]
	v_mfma_f32_16x16x4_f32 v[72:75], v133, v77, v[72:75]
	v_pk_fma_f32 v[240:241], v[116:117], v[206:207], v[240:241] op_sel:[0,1,0] op_sel_hi:[1,1,1]
	v_pk_fma_f32 v[242:243], v[118:119], v[204:205], v[242:243] op_sel:[0,0,0] op_sel_hi:[1,0,1]
	v_pk_fma_f32 v[242:243], v[120:121], v[204:205], v[242:243] op_sel:[0,1,0] op_sel_hi:[1,1,1]
	v_mfma_f32_16x16x4_f32 v[72:75], v134, v78, v[72:75]
	v_pk_fma_f32 v[242:243], v[122:123], v[206:207], v[242:243] op_sel:[0,0,0] op_sel_hi:[1,0,1]
	v_pk_fma_f32 v[242:243], v[124:125], v[206:207], v[242:243] op_sel:[0,1,0] op_sel_hi:[1,1,1]
	v_mfma_f32_16x16x4_f32 v[72:75], v135, v79, v[72:75]
	v_fmac_f32_e32 v241, v126, v240
	v_pk_fma_f32 v[242:243], v[128:129], v[240:241], v[242:243] op_sel:[0,0,0] op_sel_hi:[1,0,1]
	v_pk_fma_f32 v[242:243], v[130:131], v[240:241], v[242:243] op_sel:[0,1,0] op_sel_hi:[1,1,1]
	v_fmac_f32_e32 v243, v127, v242
	v_cndmask_b32_e64 v200, v240, v84, s[98:99]
	v_cndmask_b32_e64 v201, v241, v85, s[98:99]
	v_cndmask_b32_e64 v202, v242, v86, s[98:99]
	v_cndmask_b32_e64 v203, v243, v87, s[98:99]
	v_cndmask_b32_e64 v252, v240, 0, s[98:99]
	v_cndmask_b32_e64 v253, v241, 0, s[98:99]
	v_cndmask_b32_e64 v254, v242, 0, s[98:99]
	v_cndmask_b32_e64 v255, v243, 0, s[98:99]
	v_mfma_f32_16x16x4_f32 v[208:211], v184, v200, v[208:211]
	v_mfma_f32_16x16x4_f32 v[212:215], v188, v200, v[212:215]
	v_mfma_f32_16x16x4_f32 v[216:219], v192, v200, v[216:219]
	v_mfma_f32_16x16x4_f32 v[220:223], v196, v200, v[220:223]
	v_mfma_f32_16x16x4_f32 v[208:211], v185, v201, v[208:211]
	v_mfma_f32_16x16x4_f32 v[212:215], v189, v201, v[212:215]
	v_mfma_f32_16x16x4_f32 v[216:219], v193, v201, v[216:219]
	v_mfma_f32_16x16x4_f32 v[220:223], v197, v201, v[220:223]
	v_mfma_f32_16x16x4_f32 v[208:211], v186, v202, v[208:211]
	v_mfma_f32_16x16x4_f32 v[212:215], v190, v202, v[212:215]
	v_mfma_f32_16x16x4_f32 v[216:219], v194, v202, v[216:219]
	v_mfma_f32_16x16x4_f32 v[220:223], v198, v202, v[220:223]
	v_mfma_f32_16x16x4_f32 v[208:211], v187, v203, v[208:211]
	v_mfma_f32_16x16x4_f32 v[212:215], v191, v203, v[212:215]
	v_mfma_f32_16x16x4_f32 v[216:219], v195, v203, v[216:219]
	v_mfma_f32_16x16x4_f32 v[220:223], v199, v203, v[220:223]
	v_mfma_f32_16x16x4_f32 v[248:251], v80, v252, v[240:243]
	v_mfma_f32_16x16x4_f32 v[248:251], v81, v253, v[248:251]
	v_mfma_f32_16x16x4_f32 v[248:251], v82, v254, v[248:251]
	v_mfma_f32_16x16x4_f32 v[248:251], v83, v255, v[248:251]
	s_waitcnt lgkmcnt(3)
	s_nop 2
	v_pk_mul_f32 v[208:209], v[208:209], v[88:89]
	v_pk_mul_f32 v[210:211], v[210:211], v[90:91]
	s_nop 0
	v_mfma_f32_16x16x4_f32 v[72:75], v140, v208, v[72:75]
	s_waitcnt lgkmcnt(2)
	v_pk_mul_f32 v[212:213], v[212:213], v[92:93]
	v_mfma_f32_16x16x4_f32 v[244:247], v141, v209, 0
	v_pk_mul_f32 v[214:215], v[214:215], v[94:95]
	v_mfma_f32_16x16x4_f32 v[72:75], v142, v210, v[72:75]
	s_waitcnt lgkmcnt(1)
	v_pk_mul_f32 v[216:217], v[216:217], v[96:97]
	v_mfma_f32_16x16x4_f32 v[244:247], v143, v211, v[244:247]
	v_pk_mul_f32 v[218:219], v[218:219], v[98:99]
	v_mfma_f32_16x16x4_f32 v[72:75], v144, v212, v[72:75]
	s_waitcnt lgkmcnt(0)
	v_pk_mul_f32 v[220:221], v[220:221], v[100:101]
	v_mfma_f32_16x16x4_f32 v[244:247], v145, v213, v[244:247]
	v_pk_mul_f32 v[222:223], v[222:223], v[102:103]
	v_mfma_f32_16x16x4_f32 v[72:75], v146, v214, v[72:75]
	s_mov_b64 exec, s[98:99]
	ds_write_b32 v231, v248
	ds_write_b32 v231, v249 offset:256
	ds_write_b32 v231, v250 offset:512
	ds_write_b32 v231, v251 offset:768
	s_mov_b64 exec, -1
	ds_read_b128 v[184:187], v236 offset:14080
	ds_read_b128 v[188:191], v236 offset:15104
	v_mfma_f32_16x16x4_f32 v[244:247], v147, v215, v[244:247]
	ds_read_b128 v[192:195], v236 offset:16128
	ds_read_b128 v[196:199], v236 offset:17152
	v_mfma_f32_16x16x4_f32 v[72:75], v148, v216, v[72:75]
	v_mfma_f32_16x16x4_f32 v[244:247], v149, v217, v[244:247]
	v_mfma_f32_16x16x4_f32 v[72:75], v150, v218, v[72:75]
	v_mfma_f32_16x16x4_f32 v[244:247], v151, v219, v[244:247]
	v_mfma_f32_16x16x4_f32 v[72:75], v152, v220, v[72:75]
	v_mfma_f32_16x16x4_f32 v[244:247], v153, v221, v[244:247]
	v_mfma_f32_16x16x4_f32 v[72:75], v154, v222, v[72:75]
	v_mfma_f32_16x16x4_f32 v[244:247], v155, v223, v[244:247]
	s_nop 9
	v_pk_add_f32 v[72:73], v[72:73], v[244:245]
	v_pk_add_f32 v[74:75], v[74:75], v[246:247]
	v_fmac_f32_e32 v73, v156, v72
	v_pk_fma_f32 v[74:75], v[158:159], v[72:73], v[74:75] op_sel:[0,0,0] op_sel_hi:[1,0,1]
	v_pk_fma_f32 v[74:75], v[160:161], v[72:73], v[74:75] op_sel:[0,1,0] op_sel_hi:[1,1,1]
	v_fmac_f32_e32 v75, v157, v74
	ds_bpermute_b32 v204, v232, v72
	ds_bpermute_b32 v205, v232, v73
	ds_bpermute_b32 v206, v232, v74
	ds_bpermute_b32 v207, v232, v75
	ds_read_b128 v[140:143], v226 offset:9984
	ds_read_b128 v[144:147], v226 offset:10048
	ds_read_b128 v[148:151], v226 offset:10112
	ds_read_b128 v[152:155], v226 offset:10176
	s_waitcnt lgkmcnt(6)
	v_pk_fma_f32 v[72:73], v[162:163], v[204:205], v[72:73] op_sel:[0,0,0] op_sel_hi:[1,0,1]
	v_pk_fma_f32 v[72:73], v[164:165], v[204:205], v[72:73] op_sel:[0,1,0] op_sel_hi:[1,1,1]
	s_waitcnt lgkmcnt(4)
	v_pk_fma_f32 v[72:73], v[166:167], v[206:207], v[72:73] op_sel:[0,0,0] op_sel_hi:[1,0,1]
	v_pk_fma_f32 v[72:73], v[168:169], v[206:207], v[72:73] op_sel:[0,1,0] op_sel_hi:[1,1,1]
	v_pk_fma_f32 v[74:75], v[170:171], v[204:205], v[74:75] op_sel:[0,0,0] op_sel_hi:[1,0,1]
	v_pk_fma_f32 v[74:75], v[172:173], v[204:205], v[74:75] op_sel:[0,1,0] op_sel_hi:[1,1,1]
	v_pk_fma_f32 v[74:75], v[174:175], v[206:207], v[74:75] op_sel:[0,0,0] op_sel_hi:[1,0,1]
	v_pk_fma_f32 v[74:75], v[176:177], v[206:207], v[74:75] op_sel:[0,1,0] op_sel_hi:[1,1,1]
	v_fmac_f32_e32 v73, v178, v72
	v_pk_fma_f32 v[74:75], v[180:181], v[72:73], v[74:75] op_sel:[0,0,0] op_sel_hi:[1,0,1]
	v_pk_fma_f32 v[74:75], v[182:183], v[72:73], v[74:75] op_sel:[0,1,0] op_sel_hi:[1,1,1]
	v_fmac_f32_e32 v75, v179, v74
	v_cndmask_b32_e64 v200, v72, v136, s[98:99]
	v_cndmask_b32_e64 v201, v73, v137, s[98:99]
	v_cndmask_b32_e64 v202, v74, v138, s[98:99]
	v_cndmask_b32_e64 v203, v75, v139, s[98:99]
	v_cndmask_b32_e64 v252, v72, 0, s[98:99]
	v_cndmask_b32_e64 v253, v73, 0, s[98:99]
	v_cndmask_b32_e64 v254, v74, 0, s[98:99]
	v_cndmask_b32_e64 v255, v75, 0, s[98:99]
	v_mfma_f32_16x16x4_f32 v[208:211], v184, v200, v[208:211]
	v_mfma_f32_16x16x4_f32 v[212:215], v188, v200, v[212:215]
	v_mfma_f32_16x16x4_f32 v[216:219], v192, v200, v[216:219]
	v_mfma_f32_16x16x4_f32 v[220:223], v196, v200, v[220:223]
	v_mfma_f32_16x16x4_f32 v[208:211], v185, v201, v[208:211]
	v_mfma_f32_16x16x4_f32 v[212:215], v189, v201, v[212:215]
	v_mfma_f32_16x16x4_f32 v[216:219], v193, v201, v[216:219]
	v_mfma_f32_16x16x4_f32 v[220:223], v197, v201, v[220:223]
	v_mfma_f32_16x16x4_f32 v[208:211], v186, v202, v[208:211]
	v_mfma_f32_16x16x4_f32 v[212:215], v190, v202, v[212:215]
	v_mfma_f32_16x16x4_f32 v[216:219], v194, v202, v[216:219]
	v_mfma_f32_16x16x4_f32 v[220:223], v198, v202, v[220:223]
	v_mfma_f32_16x16x4_f32 v[208:211], v187, v203, v[208:211]
	v_mfma_f32_16x16x4_f32 v[212:215], v191, v203, v[212:215]
	v_mfma_f32_16x16x4_f32 v[216:219], v195, v203, v[216:219]
	v_mfma_f32_16x16x4_f32 v[220:223], v199, v203, v[220:223]
	v_mfma_f32_16x16x4_f32 v[248:251], v132, v252, v[72:75]
	v_mfma_f32_16x16x4_f32 v[248:251], v133, v253, v[248:251]
	v_mfma_f32_16x16x4_f32 v[248:251], v134, v254, v[248:251]
	v_mfma_f32_16x16x4_f32 v[248:251], v135, v255, v[248:251]
	s_mov_b32 s100, 0x6100
	s_cmp_eq_u32 s23, 0
	s_cselect_b32 s100, s100, 0x4e00
	v_add_u32_e32 v225, s100, v225
	v_add_u32_e32 v236, s100, v236
	v_add_u32_e32 v226, s100, v226
	v_add_u32_e32 v227, s100, v227
	v_add_u32_e32 v228, s100, v228
	v_add_u32_e32 v229, s100, v229
	ds_read_b128 v[80:83], v225 offset:8448
	ds_read_b32 v84, v230 offset:4096
	ds_read_b32 v85, v230 offset:4352
	ds_read_b32 v86, v230 offset:4608
	ds_read_b32 v87, v230 offset:4864
	ds_read_b128 v[88:91], v225
	ds_read_b128 v[92:95], v225 offset:1024
	ds_read_b128 v[96:99], v225 offset:2048
	ds_read_b128 v[100:103], v225 offset:3072
	ds_read_b32 v104, v227 offset:4
	ds_read_b32 v105, v227 offset:76
	ds_read_b64 v[106:107], v227 offset:8
	ds_read_b64 v[108:109], v227 offset:40
	ds_read_b32 v126, v229 offset:4
	ds_read_b32 v127, v229 offset:76
	ds_read_b64 v[128:129], v229 offset:8
	ds_read_b64 v[130:131], v229 offset:40
	ds_read_b64 v[110:111], v228
	ds_read_b64 v[112:113], v228 offset:32
	ds_read_b64 v[114:115], v228 offset:64
	ds_read_b64 v[116:117], v228 offset:96
	ds_read_b64 v[118:119], v228 offset:8
	ds_read_b64 v[120:121], v228 offset:40
	ds_read_b64 v[122:123], v228 offset:72
	ds_read_b64 v[124:125], v228 offset:104
	s_waitcnt lgkmcnt(15)
	v_cndmask_b32_e64 v76, 0, v84, s[98:99]
	v_cndmask_b32_e64 v77, 0, v85, s[98:99]
	v_cndmask_b32_e64 v78, 0, v86, s[98:99]
	v_cndmask_b32_e64 v79, 0, v87, s[98:99]
	v_mfma_f32_16x16x4_f32 v[240:243], v80, v76, 0
	v_mfma_f32_16x16x4_f32 v[240:243], v81, v77, v[240:243]
	v_mfma_f32_16x16x4_f32 v[240:243], v82, v78, v[240:243]
	v_mfma_f32_16x16x4_f32 v[240:243], v83, v79, v[240:243]
	v_pk_mul_f32 v[208:209], v[208:209], v[140:141]
	v_pk_mul_f32 v[210:211], v[210:211], v[142:143]
	s_nop 0
	v_mfma_f32_16x16x4_f32 v[240:243], v88, v208, v[240:243]
	v_pk_mul_f32 v[212:213], v[212:213], v[144:145]
	v_mfma_f32_16x16x4_f32 v[244:247], v89, v209, 0
	v_pk_mul_f32 v[214:215], v[214:215], v[146:147]
	v_mfma_f32_16x16x4_f32 v[240:243], v90, v210, v[240:243]
	v_pk_mul_f32 v[216:217], v[216:217], v[148:149]
	v_mfma_f32_16x16x4_f32 v[244:247], v91, v211, v[244:247]
	v_pk_mul_f32 v[218:219], v[218:219], v[150:151]
	v_mfma_f32_16x16x4_f32 v[240:243], v92, v212, v[240:243]
	v_pk_mul_f32 v[220:221], v[220:221], v[152:153]
	v_mfma_f32_16x16x4_f32 v[244:247], v93, v213, v[244:247]
	v_pk_mul_f32 v[222:223], v[222:223], v[154:155]
	v_mfma_f32_16x16x4_f32 v[240:243], v94, v214, v[240:243]
	s_mov_b64 exec, s[98:99]
	ds_write_b32 v231, v248 offset:2048
	ds_write_b32 v231, v249 offset:2304
	ds_write_b32 v231, v250 offset:2560
	ds_write_b32 v231, v251 offset:2816
	s_mov_b64 exec, -1
	ds_read_b128 v[184:187], v236 offset:4096
	ds_read_b128 v[188:191], v236 offset:5120
	v_mfma_f32_16x16x4_f32 v[244:247], v95, v215, v[244:247]
	ds_read_b128 v[192:195], v236 offset:6144
	ds_read_b128 v[196:199], v236 offset:7168
	v_mfma_f32_16x16x4_f32 v[240:243], v96, v216, v[240:243]
	ds_read_b128 v[132:135], v225 offset:18432
	ds_read_b32 v136, v230 offset:6144
	ds_read_b32 v137, v230 offset:6400
	ds_read_b32 v138, v230 offset:6656
	v_mfma_f32_16x16x4_f32 v[244:247], v97, v217, v[244:247]
	ds_read_b32 v139, v230 offset:6912
	ds_read_b128 v[140:143], v225 offset:9984
	ds_read_b128 v[144:147], v225 offset:11008
	ds_read_b128 v[148:151], v225 offset:12032
	v_mfma_f32_16x16x4_f32 v[240:243], v98, v218, v[240:243]
	ds_read_b128 v[152:155], v225 offset:13056
	ds_read_b32 v156, v227 offset:9988
	ds_read_b32 v157, v227 offset:10060
	ds_read_b64 v[158:159], v227 offset:9992
	v_mfma_f32_16x16x4_f32 v[244:247], v99, v219, v[244:247]
	ds_read_b64 v[160:161], v227 offset:10024
	ds_read_b32 v178, v229 offset:9988
	ds_read_b32 v179, v229 offset:10060
	ds_read_b64 v[180:181], v229 offset:9992
	v_mfma_f32_16x16x4_f32 v[240:243], v100, v220, v[240:243]
	ds_read_b64 v[182:183], v229 offset:10024
	ds_read_b64 v[162:163], v228 offset:9984
	ds_read_b64 v[164:165], v228 offset:10016
	ds_read_b64 v[166:167], v228 offset:10048
	v_mfma_f32_16x16x4_f32 v[244:247], v101, v221, v[244:247]
	ds_read_b64 v[168:169], v228 offset:10080
	ds_read_b64 v[170:171], v228 offset:9992
	ds_read_b64 v[172:173], v228 offset:10024
	ds_read_b64 v[174:175], v228 offset:10056
	v_mfma_f32_16x16x4_f32 v[240:243], v102, v222, v[240:243]
	ds_read_b64 v[176:177], v228 offset:10088
	v_mfma_f32_16x16x4_f32 v[244:247], v103, v223, v[244:247]
	s_nop 9
	v_pk_add_f32 v[240:241], v[240:241], v[244:245]
	v_pk_add_f32 v[242:243], v[242:243], v[246:247]
	v_fmac_f32_e32 v241, v104, v240
	s_waitcnt lgkmcnt(15)
	v_pk_fma_f32 v[242:243], v[106:107], v[240:241], v[242:243] op_sel:[0,0,0] op_sel_hi:[1,0,1]
	v_pk_fma_f32 v[242:243], v[108:109], v[240:241], v[242:243] op_sel:[0,1,0] op_sel_hi:[1,1,1]
	v_fmac_f32_e32 v243, v105, v242
	ds_bpermute_b32 v204, v232, v240
	ds_bpermute_b32 v205, v232, v241
	ds_bpermute_b32 v206, v232, v242
	ds_bpermute_b32 v207, v232, v243
	ds_read_b128 v[88:91], v226
	ds_read_b128 v[92:95], v226 offset:64
	ds_read_b128 v[96:99], v226 offset:128
	ds_read_b128 v[100:103], v226 offset:192
	v_cndmask_b32_e64 v76, 0, v136, s[98:99]
	v_cndmask_b32_e64 v77, 0, v137, s[98:99]
	v_cndmask_b32_e64 v78, 0, v138, s[98:99]
	v_cndmask_b32_e64 v79, 0, v139, s[98:99]
	v_mfma_f32_16x16x4_f32 v[72:75], v132, v76, 0
	s_waitcnt lgkmcnt(6)
	v_pk_fma_f32 v[240:241], v[110:111], v[204:205], v[240:241] op_sel:[0,0,0] op_sel_hi:[1,0,1]
	v_pk_fma_f32 v[240:241], v[112:113], v[204:205], v[240:241] op_sel:[0,1,0] op_sel_hi:[1,1,1]
	s_waitcnt lgkmcnt(4)
	v_pk_fma_f32 v[240:241], v[114:115], v[206:207], v[240:241] op_sel:[0,0,0] op_sel_hi:[1,0,1]
	v_mfma_f32_16x16x4_f32 v[72:75], v133, v77, v[72:75]
	v_pk_fma_f32 v[240:241], v[116:117], v[206:207], v[240:241] op_sel:[0,1,0] op_sel_hi:[1,1,1]
	v_pk_fma_f32 v[242:243], v[118:119], v[204:205], v[242:243] op_sel:[0,0,0] op_sel_hi:[1,0,1]
	v_pk_fma_f32 v[242:243], v[120:121], v[204:205], v[242:243] op_sel:[0,1,0] op_sel_hi:[1,1,1]
	v_mfma_f32_16x16x4_f32 v[72:75], v134, v78, v[72:75]
	v_pk_fma_f32 v[242:243], v[122:123], v[206:207], v[242:243] op_sel:[0,0,0] op_sel_hi:[1,0,1]
	v_pk_fma_f32 v[242:243], v[124:125], v[206:207], v[242:243] op_sel:[0,1,0] op_sel_hi:[1,1,1]
	v_mfma_f32_16x16x4_f32 v[72:75], v135, v79, v[72:75]
	v_fmac_f32_e32 v241, v126, v240
	v_pk_fma_f32 v[242:243], v[128:129], v[240:241], v[242:243] op_sel:[0,0,0] op_sel_hi:[1,0,1]
	v_pk_fma_f32 v[242:243], v[130:131], v[240:241], v[242:243] op_sel:[0,1,0] op_sel_hi:[1,1,1]
	v_fmac_f32_e32 v243, v127, v242
	v_cndmask_b32_e64 v200, v240, v84, s[98:99]
	v_cndmask_b32_e64 v201, v241, v85, s[98:99]
	v_cndmask_b32_e64 v202, v242, v86, s[98:99]
	v_cndmask_b32_e64 v203, v243, v87, s[98:99]
	v_cndmask_b32_e64 v252, v240, 0, s[98:99]
	v_cndmask_b32_e64 v253, v241, 0, s[98:99]
	v_cndmask_b32_e64 v254, v242, 0, s[98:99]
	v_cndmask_b32_e64 v255, v243, 0, s[98:99]
	v_mfma_f32_16x16x4_f32 v[208:211], v184, v200, v[208:211]
	v_mfma_f32_16x16x4_f32 v[212:215], v188, v200, v[212:215]
	v_mfma_f32_16x16x4_f32 v[216:219], v192, v200, v[216:219]
	v_mfma_f32_16x16x4_f32 v[220:223], v196, v200, v[220:223]
	v_mfma_f32_16x16x4_f32 v[208:211], v185, v201, v[208:211]
	v_mfma_f32_16x16x4_f32 v[212:215], v189, v201, v[212:215]
	v_mfma_f32_16x16x4_f32 v[216:219], v193, v201, v[216:219]
	v_mfma_f32_16x16x4_f32 v[220:223], v197, v201, v[220:223]
	v_mfma_f32_16x16x4_f32 v[208:211], v186, v202, v[208:211]
	v_mfma_f32_16x16x4_f32 v[212:215], v190, v202, v[212:215]
	v_mfma_f32_16x16x4_f32 v[216:219], v194, v202, v[216:219]
	v_mfma_f32_16x16x4_f32 v[220:223], v198, v202, v[220:223]
	v_mfma_f32_16x16x4_f32 v[208:211], v187, v203, v[208:211]
	v_mfma_f32_16x16x4_f32 v[212:215], v191, v203, v[212:215]
	v_mfma_f32_16x16x4_f32 v[216:219], v195, v203, v[216:219]
	v_mfma_f32_16x16x4_f32 v[220:223], v199, v203, v[220:223]
	v_mfma_f32_16x16x4_f32 v[248:251], v80, v252, v[240:243]
	v_mfma_f32_16x16x4_f32 v[248:251], v81, v253, v[248:251]
	v_mfma_f32_16x16x4_f32 v[248:251], v82, v254, v[248:251]
	v_mfma_f32_16x16x4_f32 v[248:251], v83, v255, v[248:251]
	s_waitcnt lgkmcnt(3)
	s_nop 2
	v_pk_mul_f32 v[208:209], v[208:209], v[88:89]
	v_pk_mul_f32 v[210:211], v[210:211], v[90:91]
	s_nop 0
	v_mfma_f32_16x16x4_f32 v[72:75], v140, v208, v[72:75]
	s_waitcnt lgkmcnt(2)
	v_pk_mul_f32 v[212:213], v[212:213], v[92:93]
	v_mfma_f32_16x16x4_f32 v[244:247], v141, v209, 0
	v_pk_mul_f32 v[214:215], v[214:215], v[94:95]
	v_mfma_f32_16x16x4_f32 v[72:75], v142, v210, v[72:75]
	s_waitcnt lgkmcnt(1)
	v_pk_mul_f32 v[216:217], v[216:217], v[96:97]
	v_mfma_f32_16x16x4_f32 v[244:247], v143, v211, v[244:247]
	v_pk_mul_f32 v[218:219], v[218:219], v[98:99]
	v_mfma_f32_16x16x4_f32 v[72:75], v144, v212, v[72:75]
	s_waitcnt lgkmcnt(0)
	v_pk_mul_f32 v[220:221], v[220:221], v[100:101]
	v_mfma_f32_16x16x4_f32 v[244:247], v145, v213, v[244:247]
	v_pk_mul_f32 v[222:223], v[222:223], v[102:103]
	v_mfma_f32_16x16x4_f32 v[72:75], v146, v214, v[72:75]
	s_mov_b64 exec, s[98:99]
	ds_write_b32 v231, v248 offset:4096
	ds_write_b32 v231, v249 offset:4352
	ds_write_b32 v231, v250 offset:4608
	ds_write_b32 v231, v251 offset:4864
	s_mov_b64 exec, -1
	ds_read_b128 v[184:187], v236 offset:14080
	ds_read_b128 v[188:191], v236 offset:15104
	v_mfma_f32_16x16x4_f32 v[244:247], v147, v215, v[244:247]
	ds_read_b128 v[192:195], v236 offset:16128
	ds_read_b128 v[196:199], v236 offset:17152
	v_mfma_f32_16x16x4_f32 v[72:75], v148, v216, v[72:75]
	v_mfma_f32_16x16x4_f32 v[244:247], v149, v217, v[244:247]
	v_mfma_f32_16x16x4_f32 v[72:75], v150, v218, v[72:75]
	v_mfma_f32_16x16x4_f32 v[244:247], v151, v219, v[244:247]
	v_mfma_f32_16x16x4_f32 v[72:75], v152, v220, v[72:75]
	v_mfma_f32_16x16x4_f32 v[244:247], v153, v221, v[244:247]
	v_mfma_f32_16x16x4_f32 v[72:75], v154, v222, v[72:75]
	v_mfma_f32_16x16x4_f32 v[244:247], v155, v223, v[244:247]
	s_nop 9
	v_pk_add_f32 v[72:73], v[72:73], v[244:245]
	v_pk_add_f32 v[74:75], v[74:75], v[246:247]
	v_fmac_f32_e32 v73, v156, v72
	v_pk_fma_f32 v[74:75], v[158:159], v[72:73], v[74:75] op_sel:[0,0,0] op_sel_hi:[1,0,1]
	v_pk_fma_f32 v[74:75], v[160:161], v[72:73], v[74:75] op_sel:[0,1,0] op_sel_hi:[1,1,1]
	v_fmac_f32_e32 v75, v157, v74
	ds_bpermute_b32 v204, v232, v72
	ds_bpermute_b32 v205, v232, v73
	ds_bpermute_b32 v206, v232, v74
	ds_bpermute_b32 v207, v232, v75
	ds_read_b128 v[140:143], v226 offset:9984
	ds_read_b128 v[144:147], v226 offset:10048
	ds_read_b128 v[148:151], v226 offset:10112
	ds_read_b128 v[152:155], v226 offset:10176
	s_waitcnt lgkmcnt(6)
	v_pk_fma_f32 v[72:73], v[162:163], v[204:205], v[72:73] op_sel:[0,0,0] op_sel_hi:[1,0,1]
	v_pk_fma_f32 v[72:73], v[164:165], v[204:205], v[72:73] op_sel:[0,1,0] op_sel_hi:[1,1,1]
	s_waitcnt lgkmcnt(4)
	v_pk_fma_f32 v[72:73], v[166:167], v[206:207], v[72:73] op_sel:[0,0,0] op_sel_hi:[1,0,1]
	v_pk_fma_f32 v[72:73], v[168:169], v[206:207], v[72:73] op_sel:[0,1,0] op_sel_hi:[1,1,1]
	v_pk_fma_f32 v[74:75], v[170:171], v[204:205], v[74:75] op_sel:[0,0,0] op_sel_hi:[1,0,1]
	v_pk_fma_f32 v[74:75], v[172:173], v[204:205], v[74:75] op_sel:[0,1,0] op_sel_hi:[1,1,1]
	v_pk_fma_f32 v[74:75], v[174:175], v[206:207], v[74:75] op_sel:[0,0,0] op_sel_hi:[1,0,1]
	v_pk_fma_f32 v[74:75], v[176:177], v[206:207], v[74:75] op_sel:[0,1,0] op_sel_hi:[1,1,1]
	v_fmac_f32_e32 v73, v178, v72
	v_pk_fma_f32 v[74:75], v[180:181], v[72:73], v[74:75] op_sel:[0,0,0] op_sel_hi:[1,0,1]
	v_pk_fma_f32 v[74:75], v[182:183], v[72:73], v[74:75] op_sel:[0,1,0] op_sel_hi:[1,1,1]
	v_fmac_f32_e32 v75, v179, v74
	v_cndmask_b32_e64 v200, v72, v136, s[98:99]
	v_cndmask_b32_e64 v201, v73, v137, s[98:99]
	v_cndmask_b32_e64 v202, v74, v138, s[98:99]
	v_cndmask_b32_e64 v203, v75, v139, s[98:99]
	v_cndmask_b32_e64 v252, v72, 0, s[98:99]
	v_cndmask_b32_e64 v253, v73, 0, s[98:99]
	v_cndmask_b32_e64 v254, v74, 0, s[98:99]
	v_cndmask_b32_e64 v255, v75, 0, s[98:99]
	v_mfma_f32_16x16x4_f32 v[208:211], v184, v200, v[208:211]
	v_mfma_f32_16x16x4_f32 v[212:215], v188, v200, v[212:215]
	v_mfma_f32_16x16x4_f32 v[216:219], v192, v200, v[216:219]
	v_mfma_f32_16x16x4_f32 v[220:223], v196, v200, v[220:223]
	v_mfma_f32_16x16x4_f32 v[208:211], v185, v201, v[208:211]
	v_mfma_f32_16x16x4_f32 v[212:215], v189, v201, v[212:215]
	v_mfma_f32_16x16x4_f32 v[216:219], v193, v201, v[216:219]
	v_mfma_f32_16x16x4_f32 v[220:223], v197, v201, v[220:223]
	v_mfma_f32_16x16x4_f32 v[208:211], v186, v202, v[208:211]
	v_mfma_f32_16x16x4_f32 v[212:215], v190, v202, v[212:215]
	v_mfma_f32_16x16x4_f32 v[216:219], v194, v202, v[216:219]
	v_mfma_f32_16x16x4_f32 v[220:223], v198, v202, v[220:223]
	v_mfma_f32_16x16x4_f32 v[208:211], v187, v203, v[208:211]
	v_mfma_f32_16x16x4_f32 v[212:215], v191, v203, v[212:215]
	v_mfma_f32_16x16x4_f32 v[216:219], v195, v203, v[216:219]
	v_mfma_f32_16x16x4_f32 v[220:223], v199, v203, v[220:223]
	v_mfma_f32_16x16x4_f32 v[248:251], v132, v252, v[72:75]
	v_mfma_f32_16x16x4_f32 v[248:251], v133, v253, v[248:251]
	v_mfma_f32_16x16x4_f32 v[248:251], v134, v254, v[248:251]
	v_mfma_f32_16x16x4_f32 v[248:251], v135, v255, v[248:251]
	s_waitcnt lgkmcnt(3)
	s_nop 2
	v_pk_mul_f32 v[208:209], v[208:209], v[140:141]
	v_pk_mul_f32 v[210:211], v[210:211], v[142:143]
	s_waitcnt lgkmcnt(2)
	v_pk_mul_f32 v[212:213], v[212:213], v[144:145]
	v_pk_mul_f32 v[214:215], v[214:215], v[146:147]
	s_waitcnt lgkmcnt(1)
	v_pk_mul_f32 v[216:217], v[216:217], v[148:149]
	v_pk_mul_f32 v[218:219], v[218:219], v[150:151]
	s_waitcnt lgkmcnt(0)
	v_pk_mul_f32 v[220:221], v[220:221], v[152:153]
	v_pk_mul_f32 v[222:223], v[222:223], v[154:155]
	s_mov_b64 exec, s[98:99]
	ds_write_b32 v231, v248 offset:6144
	ds_write_b32 v231, v249 offset:6400
	ds_write_b32 v231, v250 offset:6656
	ds_write_b32 v231, v251 offset:6912
	s_mov_b64 exec, -1
	s_branch .LBB0_655
